# phase-1 and phase-3 sample-row units: deeper staged-load queues with per-fragment waits
# baseline (speedup 1.0000x reference)
.LBB0_1020:
	s_lshr_b32 s7, s6, 2
	s_and_b32 s1, s6, 7
	s_and_b32 s0, s3, 0xc0
	s_and_b32 s7, s7, 0x3fffff8
	s_bitset1_b32 s0, 14
	s_or_b32 s1, s7, s1
	s_lshl_b32 s1, s1, 6
	v_add_lshl_u32 v2, s0, v1, 11
	v_lshl_add_u64 v[116:117], v[4:5], 0, v[2:3]
	v_add_lshl_u32 v2, s1, v1, 11
	v_lshl_add_u64 v[118:119], v[6:7], 0, v[2:3]
	s_waitcnt lgkmcnt(0)
	global_load_dwordx4 v[122:125], v[116:117], off
	global_load_dwordx4 v[126:129], v[116:117], off offset:128
	global_load_dwordx4 v[130:133], v[118:119], off
	global_load_dwordx4 v[134:137], v[118:119], off offset:128
	global_load_dwordx4 v[138:141], v[116:117], off offset:256
	global_load_dwordx4 v[142:145], v[116:117], off offset:384
	global_load_dwordx4 v[146:149], v[118:119], off offset:256
	global_load_dwordx4 v[150:153], v[118:119], off offset:384
	global_load_dwordx4 v[154:157], v[116:117], off offset:512
	global_load_dwordx4 v[168:171], v[116:117], off offset:640
	global_load_dwordx4 v[172:175], v[118:119], off offset:512
	global_load_dwordx4 v[176:179], v[118:119], off offset:640
	global_load_dwordx4 v[180:183], v[116:117], off offset:768
	global_load_dwordx4 v[184:187], v[116:117], off offset:896
	global_load_dwordx4 v[188:191], v[118:119], off offset:768
	global_load_dwordx4 v[192:195], v[118:119], off offset:896
	global_load_dwordx4 v[196:199], v[116:117], off offset:1024
	global_load_dwordx4 v[206:209], v[116:117], off offset:1152
	global_load_dwordx4 v[210:213], v[118:119], off offset:1024
	global_load_dwordx4 v[214:217], v[118:119], off offset:1152
	global_load_dwordx4 v[218:221], v[116:117], off offset:1280
	global_load_dwordx4 v[222:225], v[116:117], off offset:1408
	global_load_dwordx4 v[226:229], v[118:119], off offset:1280
	global_load_dwordx4 v[230:233], v[118:119], off offset:1408
	v_add_u32_e32 v19, s0, v9
	v_lshlrev_b32_e32 v2, 11, v19
	s_waitcnt vmcnt(23)
	ds_write_b128 v8, v[122:125]
	s_waitcnt vmcnt(22)
	ds_write_b128 v8, v[126:129] offset:128
	s_waitcnt vmcnt(21)
	ds_write_b128 v8, v[130:133] offset:34816
	s_waitcnt vmcnt(20)
	ds_write_b128 v8, v[134:137] offset:34944
	s_waitcnt lgkmcnt(0)
	s_barrier
	ds_read_b128 v[20:23], v14 offset:34816
	ds_read_b128 v[24:27], v14 offset:43520
	ds_read_b128 v[28:31], v10
	ds_read_b128 v[32:35], v10 offset:64
	ds_read_b128 v[84:87], v14 offset:34880
	global_load_dwordx4 v[234:237], v[116:117], off offset:1536
	global_load_dwordx4 v[238:241], v[116:117], off offset:1664
	ds_read_b128 v[96:99], v14 offset:43584
	s_waitcnt lgkmcnt(3)
	v_mfma_f32_16x16x32_bf16 v[20:23], v[20:23], v[28:31], 0
	v_mfma_f32_16x16x32_bf16 v[24:27], v[24:27], v[28:31], 0
	global_load_dwordx4 v[122:125], v[118:119], off offset:1536
	global_load_dwordx4 v[126:129], v[118:119], off offset:1664
	ds_read_b128 v[104:107], v14 offset:34944
	s_waitcnt lgkmcnt(2)
	v_mfma_f32_16x16x32_bf16 v[20:23], v[84:87], v[32:35], v[20:23]
	ds_read_b128 v[84:87], v14 offset:43648
	ds_read_b128 v[108:111], v10 offset:128
	ds_read_b128 v[112:115], v10 offset:192
	s_waitcnt lgkmcnt(4)
	v_mfma_f32_16x16x32_bf16 v[24:27], v[96:99], v[32:35], v[24:27]
	ds_read_b128 v[32:35], v14 offset:35008
	ds_read_b128 v[96:99], v14 offset:43712
	s_waitcnt vmcnt(23)
	ds_write_b128 v8, v[138:141] offset:17408
	s_waitcnt vmcnt(22)
	ds_write_b128 v8, v[142:145] offset:17536
	s_waitcnt vmcnt(21)
	ds_write_b128 v8, v[146:149] offset:52224
	s_waitcnt vmcnt(20)
	ds_write_b128 v8, v[150:153] offset:52352
	s_waitcnt lgkmcnt(7)
	v_mfma_f32_16x16x32_bf16 v[20:23], v[104:107], v[108:111], v[20:23]
	s_waitcnt lgkmcnt(0)
	s_barrier
	v_mfma_f32_16x16x32_bf16 v[24:27], v[84:87], v[108:111], v[24:27]
	v_mfma_f32_16x16x32_bf16 v[20:23], v[32:35], v[112:115], v[20:23]
	ds_read_b128 v[32:35], v12 offset:52224
	ds_read_b128 v[36:39], v12 offset:60928
	ds_read_b128 v[40:43], v11
	ds_read_b128 v[44:47], v11 offset:64
	ds_read_b128 v[48:51], v12 offset:52288
	v_mfma_f32_16x16x32_bf16 v[24:27], v[96:99], v[112:115], v[24:27]
	s_waitcnt lgkmcnt(2)
	v_mfma_f32_16x16x32_bf16 v[20:23], v[32:35], v[40:43], v[20:23]
	global_load_dwordx4 v[130:133], v[116:117], off offset:1792
	global_load_dwordx4 v[134:137], v[116:117], off offset:1920
	ds_read_b128 v[96:99], v12 offset:60992
	v_mfma_f32_16x16x32_bf16 v[24:27], v[36:39], v[40:43], v[24:27]
	global_load_dwordx4 v[138:141], v[118:119], off offset:1792
	global_load_dwordx4 v[142:145], v[118:119], off offset:1920
	ds_read_b128 v[104:107], v12 offset:52352
	s_waitcnt lgkmcnt(2)
	v_mfma_f32_16x16x32_bf16 v[20:23], v[48:51], v[44:47], v[20:23]
	ds_read_b128 v[48:51], v12 offset:61056
	ds_read_b128 v[108:111], v11 offset:128
	ds_read_b128 v[112:115], v11 offset:192
	s_waitcnt lgkmcnt(4)
	v_mfma_f32_16x16x32_bf16 v[24:27], v[96:99], v[44:47], v[24:27]
	ds_read_b128 v[44:47], v12 offset:52416
	ds_read_b128 v[96:99], v12 offset:61120
	s_waitcnt vmcnt(23)
	ds_write_b128 v8, v[154:157]
	s_waitcnt vmcnt(22)
	ds_write_b128 v8, v[168:171] offset:128
	s_waitcnt vmcnt(21)
	ds_write_b128 v8, v[172:175] offset:34816
	s_waitcnt vmcnt(20)
	ds_write_b128 v8, v[176:179] offset:34944
	s_waitcnt lgkmcnt(7)
	v_mfma_f32_16x16x32_bf16 v[20:23], v[104:107], v[108:111], v[20:23]
	s_waitcnt lgkmcnt(0)
	s_barrier
	v_mfma_f32_16x16x32_bf16 v[24:27], v[48:51], v[108:111], v[24:27]
	v_mfma_f32_16x16x32_bf16 v[20:23], v[44:47], v[112:115], v[20:23]
	ds_read_b128 v[44:47], v14 offset:34816
	ds_read_b128 v[48:51], v14 offset:43520
	ds_read_b128 v[52:55], v10
	ds_read_b128 v[56:59], v10 offset:64
	ds_read_b128 v[60:63], v14 offset:34880
	v_mfma_f32_16x16x32_bf16 v[24:27], v[96:99], v[112:115], v[24:27]
	s_waitcnt lgkmcnt(2)
	v_mfma_f32_16x16x32_bf16 v[20:23], v[44:47], v[52:55], v[20:23]
	ds_read_b128 v[96:99], v14 offset:43584
	v_mfma_f32_16x16x32_bf16 v[24:27], v[48:51], v[52:55], v[24:27]
	ds_read_b128 v[104:107], v14 offset:34944
	s_waitcnt lgkmcnt(2)
	v_mfma_f32_16x16x32_bf16 v[20:23], v[60:63], v[56:59], v[20:23]
	ds_read_b128 v[60:63], v14 offset:43648
	ds_read_b128 v[108:111], v10 offset:128
	ds_read_b128 v[112:115], v10 offset:192
	s_waitcnt lgkmcnt(4)
	v_mfma_f32_16x16x32_bf16 v[24:27], v[96:99], v[56:59], v[24:27]
	ds_read_b128 v[56:59], v14 offset:35008
	ds_read_b128 v[96:99], v14 offset:43712
	s_waitcnt vmcnt(19)
	ds_write_b128 v8, v[180:183] offset:17408
	s_waitcnt vmcnt(18)
	ds_write_b128 v8, v[184:187] offset:17536
	s_waitcnt vmcnt(17)
	ds_write_b128 v8, v[188:191] offset:52224
	s_waitcnt vmcnt(16)
	ds_write_b128 v8, v[192:195] offset:52352
	s_waitcnt lgkmcnt(7)
	v_mfma_f32_16x16x32_bf16 v[20:23], v[104:107], v[108:111], v[20:23]
	s_waitcnt lgkmcnt(0)
	s_barrier
	v_mfma_f32_16x16x32_bf16 v[20:23], v[56:59], v[112:115], v[20:23]
	ds_read_b128 v[56:59], v12 offset:52224
	v_mfma_f32_16x16x32_bf16 v[24:27], v[60:63], v[108:111], v[24:27]
	ds_read_b128 v[60:63], v11
	ds_read_b128 v[68:71], v11 offset:64
	ds_read_b128 v[72:75], v12 offset:52288
	v_mfma_f32_16x16x32_bf16 v[24:27], v[96:99], v[112:115], v[24:27]
	s_waitcnt lgkmcnt(2)
	v_mfma_f32_16x16x32_bf16 v[20:23], v[56:59], v[60:63], v[20:23]
	ds_read_b128 v[56:59], v12 offset:60928
	ds_read_b128 v[76:79], v12 offset:60992
	s_waitcnt lgkmcnt(1)
	v_mfma_f32_16x16x32_bf16 v[24:27], v[56:59], v[60:63], v[24:27]
	ds_read_b128 v[56:59], v12 offset:52352
	v_mfma_f32_16x16x32_bf16 v[20:23], v[72:75], v[68:71], v[20:23]
	s_waitcnt lgkmcnt(1)
	v_mfma_f32_16x16x32_bf16 v[24:27], v[76:79], v[68:71], v[24:27]
	ds_read_b128 v[60:63], v11 offset:128
	ds_read_b128 v[68:71], v11 offset:192
	ds_read_b128 v[72:75], v12 offset:52416
	s_waitcnt lgkmcnt(2)
	v_mfma_f32_16x16x32_bf16 v[20:23], v[56:59], v[60:63], v[20:23]
	ds_read_b128 v[56:59], v12 offset:61056
	ds_read_b128 v[76:79], v12 offset:61120
	s_waitcnt lgkmcnt(1)
	v_mfma_f32_16x16x32_bf16 v[24:27], v[56:59], v[60:63], v[24:27]
	s_waitcnt vmcnt(15)
	ds_write_b128 v8, v[196:199]
	s_waitcnt vmcnt(14)
	ds_write_b128 v8, v[206:209] offset:128
	s_waitcnt vmcnt(13)
	ds_write_b128 v8, v[210:213] offset:34816
	s_waitcnt vmcnt(12)
	ds_write_b128 v8, v[214:217] offset:34944
	s_waitcnt lgkmcnt(0)
	s_barrier
	ds_read_b128 v[28:31], v14 offset:34816
	v_mfma_f32_16x16x32_bf16 v[20:23], v[72:75], v[68:71], v[20:23]
	v_mfma_f32_16x16x32_bf16 v[24:27], v[76:79], v[68:71], v[24:27]
	ds_read_b128 v[68:71], v10
	ds_read_b128 v[72:75], v10 offset:64
	ds_read_b128 v[76:79], v14 offset:34880
	s_waitcnt lgkmcnt(2)
	v_mfma_f32_16x16x32_bf16 v[20:23], v[28:31], v[68:71], v[20:23]
	ds_read_b128 v[28:31], v14 offset:43520
	ds_read_b128 v[88:91], v14 offset:43584
	s_waitcnt lgkmcnt(1)
	v_mfma_f32_16x16x32_bf16 v[24:27], v[28:31], v[68:71], v[24:27]
	ds_read_b128 v[28:31], v14 offset:34944
	v_mfma_f32_16x16x32_bf16 v[20:23], v[76:79], v[72:75], v[20:23]
	ds_read_b128 v[68:71], v14 offset:43648
	ds_read_b128 v[76:79], v10 offset:128
	ds_read_b128 v[92:95], v10 offset:192
	s_waitcnt lgkmcnt(4)
	v_mfma_f32_16x16x32_bf16 v[24:27], v[88:91], v[72:75], v[24:27]
	ds_read_b128 v[72:75], v14 offset:35008
	ds_read_b128 v[88:91], v14 offset:43712
	s_waitcnt vmcnt(11)
	ds_write_b128 v8, v[218:221] offset:17408
	s_waitcnt vmcnt(10)
	ds_write_b128 v8, v[222:225] offset:17536
	s_waitcnt vmcnt(9)
	ds_write_b128 v8, v[226:229] offset:52224
	s_waitcnt vmcnt(8)
	ds_write_b128 v8, v[230:233] offset:52352
	s_waitcnt lgkmcnt(7)
	v_mfma_f32_16x16x32_bf16 v[20:23], v[28:31], v[76:79], v[20:23]
	s_waitcnt lgkmcnt(0)
	s_barrier
	ds_read_b128 v[28:31], v12 offset:52224
	v_mfma_f32_16x16x32_bf16 v[24:27], v[68:71], v[76:79], v[24:27]
	ds_read_b128 v[32:35], v11
	ds_read_b128 v[36:39], v11 offset:64
	ds_read_b128 v[40:43], v12 offset:52288
	v_mfma_f32_16x16x32_bf16 v[20:23], v[72:75], v[92:95], v[20:23]
	v_mfma_f32_16x16x32_bf16 v[24:27], v[88:91], v[92:95], v[24:27]
	s_waitcnt lgkmcnt(2)
	v_mfma_f32_16x16x32_bf16 v[20:23], v[28:31], v[32:35], v[20:23]
	ds_read_b128 v[28:31], v12 offset:60928
	ds_read_b128 v[68:71], v12 offset:60992
	s_waitcnt lgkmcnt(1)
	v_mfma_f32_16x16x32_bf16 v[24:27], v[28:31], v[32:35], v[24:27]
	ds_read_b128 v[28:31], v12 offset:52352
	v_mfma_f32_16x16x32_bf16 v[20:23], v[40:43], v[36:39], v[20:23]
	s_waitcnt lgkmcnt(1)
	v_mfma_f32_16x16x32_bf16 v[24:27], v[68:71], v[36:39], v[24:27]
	ds_read_b128 v[32:35], v11 offset:128
	ds_read_b128 v[36:39], v11 offset:192
	ds_read_b128 v[40:43], v12 offset:52416
	s_waitcnt lgkmcnt(2)
	v_mfma_f32_16x16x32_bf16 v[20:23], v[28:31], v[32:35], v[20:23]
	ds_read_b128 v[28:31], v12 offset:61056
	ds_read_b128 v[68:71], v12 offset:61120
	s_waitcnt vmcnt(7)
	ds_write_b128 v8, v[234:237]
	s_waitcnt vmcnt(6)
	ds_write_b128 v8, v[238:241] offset:128
	s_waitcnt vmcnt(5)
	ds_write_b128 v8, v[122:125] offset:34816
	s_waitcnt vmcnt(4)
	ds_write_b128 v8, v[126:129] offset:34944
	s_waitcnt lgkmcnt(0)
	v_mfma_f32_16x16x32_bf16 v[24:27], v[28:31], v[32:35], v[24:27]
	s_barrier
	ds_read_b128 v[28:31], v14 offset:34816
	v_mfma_f32_16x16x32_bf16 v[20:23], v[40:43], v[36:39], v[20:23]
	v_mfma_f32_16x16x32_bf16 v[24:27], v[68:71], v[36:39], v[24:27]
	ds_read_b128 v[32:35], v10
	ds_read_b128 v[36:39], v10 offset:64
	ds_read_b128 v[40:43], v14 offset:34880
	s_waitcnt lgkmcnt(2)
	v_mfma_f32_16x16x32_bf16 v[20:23], v[28:31], v[32:35], v[20:23]
	ds_read_b128 v[28:31], v14 offset:43520
	ds_read_b128 v[44:47], v14 offset:43584
	s_waitcnt lgkmcnt(1)
	v_mfma_f32_16x16x32_bf16 v[24:27], v[28:31], v[32:35], v[24:27]
	ds_read_b128 v[28:31], v14 offset:34944
	v_mfma_f32_16x16x32_bf16 v[20:23], v[40:43], v[36:39], v[20:23]
	s_waitcnt lgkmcnt(1)
	v_mfma_f32_16x16x32_bf16 v[24:27], v[44:47], v[36:39], v[24:27]
	ds_read_b128 v[32:35], v10 offset:128
	ds_read_b128 v[36:39], v10 offset:192
	ds_read_b128 v[40:43], v14 offset:35008
	s_waitcnt lgkmcnt(2)
	v_mfma_f32_16x16x32_bf16 v[20:23], v[28:31], v[32:35], v[20:23]
	ds_read_b128 v[28:31], v14 offset:43648
	ds_read_b128 v[44:47], v14 offset:43712
	s_waitcnt vmcnt(3)
	ds_write_b128 v8, v[130:133] offset:17408
	s_waitcnt vmcnt(2)
	ds_write_b128 v8, v[134:137] offset:17536
	s_waitcnt vmcnt(1)
	ds_write_b128 v8, v[138:141] offset:52224
	s_waitcnt vmcnt(0)
	ds_write_b128 v8, v[142:145] offset:52352
	s_waitcnt lgkmcnt(0)
	v_mfma_f32_16x16x32_bf16 v[24:27], v[28:31], v[32:35], v[24:27]
	s_barrier
	ds_read_b128 v[28:31], v12 offset:52224
	v_mfma_f32_16x16x32_bf16 v[20:23], v[40:43], v[36:39], v[20:23]
	v_mfma_f32_16x16x32_bf16 v[24:27], v[44:47], v[36:39], v[24:27]
	ds_read_b128 v[32:35], v11
	ds_read_b128 v[36:39], v11 offset:64
	ds_read_b128 v[40:43], v12 offset:52288
	s_waitcnt lgkmcnt(2)
	v_mfma_f32_16x16x32_bf16 v[20:23], v[28:31], v[32:35], v[20:23]
	ds_read_b128 v[28:31], v12 offset:60928
	ds_read_b128 v[44:47], v12 offset:60992
	s_waitcnt lgkmcnt(1)
	v_mfma_f32_16x16x32_bf16 v[24:27], v[28:31], v[32:35], v[24:27]
	ds_read_b128 v[28:31], v12 offset:52352
	v_mfma_f32_16x16x32_bf16 v[20:23], v[40:43], v[36:39], v[20:23]
	s_waitcnt lgkmcnt(1)
	v_mfma_f32_16x16x32_bf16 v[24:27], v[44:47], v[36:39], v[24:27]
	ds_read_b128 v[32:35], v11 offset:128
	ds_read_b128 v[36:39], v11 offset:192
	ds_read_b128 v[40:43], v12 offset:52416
	s_waitcnt lgkmcnt(2)
	v_mfma_f32_16x16x32_bf16 v[20:23], v[28:31], v[32:35], v[20:23]
	ds_read_b128 v[28:31], v12 offset:61056
	ds_read_b128 v[44:47], v12 offset:61120
	s_waitcnt lgkmcnt(0)
	s_barrier
	v_mfma_f32_16x16x32_bf16 v[24:27], v[28:31], v[32:35], v[24:27]
	v_or_b32_e32 v28, s1, v13
	v_mov_b32_e32 v29, v3
	v_lshl_add_u64 v[30:31], s[58:59], 0, v[2:3]
	v_lshlrev_b64 v[28:29], 1, v[28:29]
	v_lshl_add_u64 v[30:31], v[30:31], 0, v[28:29]
	global_load_dwordx2 v[32:33], v[30:31], off
	v_mfma_f32_16x16x32_bf16 v[20:23], v[40:43], v[36:39], v[20:23]
	global_load_dwordx2 v[30:31], v[30:31], off offset:64
	v_cmp_lt_i32_e64 s[0:1], v16, v17
	s_waitcnt vmcnt(1)
	v_lshlrev_b32_e32 v34, 16, v32
	v_and_b32_e32 v35, 0xffff0000, v32
	v_lshlrev_b32_e32 v32, 16, v33
	v_and_b32_e32 v33, 0xffff0000, v33
	s_nop 0
	v_pk_fma_f32 v[20:21], v[34:35], s[4:5], v[20:21] op_sel_hi:[1,0,1]
	v_mfma_f32_16x16x32_bf16 v[24:27], v[44:47], v[36:39], v[24:27]
	v_fma_f32 v22, v32, s4, v22
	v_fma_f32 v23, v33, s4, v23
	v_cvt_pk_bf16_f32 v32, v20, v21
	v_lshl_add_u64 v[34:35], s[94:95], 0, v[2:3]
	v_add_f32_e32 v2, v20, v21
	v_mul_f32_e32 v21, v21, v21
	v_fmac_f32_e32 v21, v20, v20
	v_mul_f32_e32 v20, v23, v23
	v_lshl_add_u64 v[28:29], v[34:35], 0, v[28:29]
	v_add_f32_e32 v34, v22, v23
	v_fmac_f32_e32 v20, v22, v22
	v_cvt_pk_bf16_f32 v33, v22, v23
	v_add_f32_e32 v2, v2, v34
	v_add_f32_e32 v34, v21, v20
	s_waitcnt vmcnt(0)
	v_lshlrev_b32_e32 v20, 16, v30
	v_and_b32_e32 v21, 0xffff0000, v30
	v_lshlrev_b32_e32 v22, 16, v31
	v_and_b32_e32 v23, 0xffff0000, v31
	v_pk_fma_f32 v[26:27], v[22:23], s[4:5], v[26:27] op_sel_hi:[1,0,1]
	v_pk_fma_f32 v[24:25], v[20:21], s[4:5], v[24:25] op_sel_hi:[1,0,1]
	v_add_f32_e32 v21, v26, v27
	v_add_f32_e32 v20, v24, v25
	v_add_f32_e32 v2, 0, v2
	v_add_f32_e32 v20, v20, v21
	v_add_f32_e32 v2, v2, v20
	v_mul_f32_e32 v20, v25, v25
	v_mul_f32_e32 v23, v27, v27
	v_fmac_f32_e32 v20, v24, v24
	v_fmac_f32_e32 v23, v26, v26
	v_cndmask_b32_e64 v21, v15, v16, s[0:1]
	v_add_f32_e32 v20, v20, v23
	v_lshlrev_b32_e32 v21, 2, v21
	v_add_f32_e32 v23, v34, v20
	ds_bpermute_b32 v22, v21, v2
	ds_bpermute_b32 v21, v21, v23
	v_cmp_lt_i32_e64 s[0:1], v18, v17
	global_store_dwordx2 v[28:29], v[32:33], off
	v_cvt_pk_bf16_f32 v24, v24, v25
	s_waitcnt lgkmcnt(1)
	v_add_f32_e32 v2, v2, v22
	v_cndmask_b32_e64 v20, v15, v18, s[0:1]
	v_lshlrev_b32_e32 v22, 2, v20
	s_waitcnt lgkmcnt(0)
	v_add_f32_e32 v21, v23, v21
	ds_bpermute_b32 v20, v22, v2
	ds_bpermute_b32 v22, v22, v21
	v_cvt_pk_bf16_f32 v25, v26, v27
	global_store_dwordx2 v[28:29], v[24:25], off offset:64
	s_and_saveexec_b64 s[0:1], vcc
	s_cbranch_execz .LBB0_1019
	s_waitcnt lgkmcnt(1)
	v_add_f32_e32 v2, v2, v20
	v_lshlrev_b32_e32 v19, 3, v19
	s_waitcnt lgkmcnt(0)
	v_add_f32_e32 v21, v21, v22
	global_atomic_add_f32 v19, v2, s[82:83]
	global_atomic_add_f32 v19, v21, s[82:83] offset:4
	s_branch .LBB0_1019
